# K-loop: end-of-MFMA-block barrier signalled 2 MFMAs early with the tail MFMAs at priority 2 (hand-off latency overlap)
# baseline (speedup 1.0000x reference)
; #define PG8_STAGE(bufoff, gbase, voff) do { _Pragma("unroll") for (int _i = 0; _i < 2; ++_i) \
;         __builtin_amdgcn_global_load_lds((const unsigned*)((const char*)(gbase) + (voff)[_i]), (PG8_LAS unsigned*)(lds + (bufoff) + ldsw + _i * 8192), 16, 0, 0); } while (0)
; #define PG8_LDA(dst, b, h) do { _Pragma("unroll") for (int m = 0; m < 4; ++m) _Pragma("unroll") for (int k = 0; k < 2; ++k) dst[m][k] = *(const PG8_LAS bf16x8*)(lds + PG8_SA(b, h) + aoff + m * 2048 + k * 1024); } while (0)
; #define PG8_LDB(dst, b, h) do { _Pragma("unroll") for (int n = 0; n < 2; ++n) _Pragma("unroll") for (int k = 0; k < 2; ++k) dst[n][k] = *(const PG8_LAS bf16x8*)(lds + PG8_SB(b, h) + boff + n * 2048 + k * 1024); } while (0)
; #define PG8_MMA(ai, bj, At, Bt) do { __builtin_amdgcn_s_setprio(1); _Pragma("unroll") for (int m = 0; m < 4; ++m) _Pragma("unroll") for (int n = 0; n < 2; ++n) _Pragma("unroll") for (int k = 0; k < 2; ++k) \
;         acc[ai][bj][m][n] = __builtin_amdgcn_mfma_f32_16x16x32_bf16(Bt[n][k], At[m][k], acc[ai][bj][m][n], 0, 0, 0); __builtin_amdgcn_s_setprio(0); } while (0)
; #define PG8_WAIT_V(n) asm volatile("s_waitcnt vmcnt(" #n ")" ::: "memory")
; #define PG8_WAIT_L(n) asm volatile("s_waitcnt lgkmcnt(" #n ")" ::: "memory")
; template <class Epi, class Sched, bool ALIGN_EPI = false, bool SP2 = false>
; __device__ __forceinline__ void gemm_phase(PG8_LAS unsigned char* lds, const Gemm g, const Sched& S, const Epi& E) {
;     ...
;             const bool last = (t == nt - 2);
;             const char* a1 = cA + (size_t)(t + 1) * kstep;
;             const char* a2 = last ? nA : cA + (size_t)(t + 2) * kstep; const char* b2 = last ? nB : cB + (size_t)(t + 2) * kstep;
;             const char* a3 = a2 + kstep; const char* b3 = b2 + kstep;
;             if (last && has_next) S.a_ready(nxt);
;             if constexpr (SP2) {
;             PG8_LDB(B0, 0, 0); PG8_LDB(B1, 0, 1); PG8_SCHED; PG8_LDA(At, 0, 0); PG8_STAGE(PG8_SA(1, 1), a1 + hstep, voffA);
;             PG8_WAIT_V(8); PG8_WAIT_L(0); PG8_BAR; PG8_MMA(0, 0, At, B0); PG8_MMA(0, 1, At, B1); PG8_BAR; PG8_SCHED;
;             PG8_LDA(At, 0, 1); PG8_STAGE(PG8_SB(0, 0), b2, voffB); PG8_STAGE(PG8_SB(0, 1), b2 + hstep, voffB); PG8_STAGE(PG8_SA(0, 0), a2, voffA);
;             PG8_WAIT_V(8); PG8_WAIT_L(0); PG8_BAR; PG8_MMA(1, 0, At, B0); PG8_MMA(1, 1, At, B1); PG8_BAR; PG8_SCHED;
.LBB0_56:
	s_add_i32 s2, s34, 2
	s_add_u32 s35, s28, s30
	s_addc_u32 s62, s29, s31
	s_add_u32 s63, s35, 0x100
	s_addc_u32 s35, s62, 0
	s_add_u32 s62, s60, s30
	s_addc_u32 s64, s61, s31
	s_add_i32 s65, 0, 0x10000
	s_cmp_eq_u32 s48, s34
	s_cselect_b32 s35, s1, s35
	s_cselect_b32 s34, s0, s63
	v_add_u32_e32 v0, s65, v188
	s_cselect_b32 s63, s27, s64
	s_cselect_b32 s62, s26, s62
	s_add_i32 s64, 0, 0x14000
	ds_read_b128 v[132:135], v0
	ds_read_b128 v[136:139], v0 offset:1024
	ds_read_b128 v[140:143], v0 offset:2048
	ds_read_b128 v[144:147], v0 offset:3072
	v_add_u32_e32 v0, s64, v188
	ds_read_b128 v[148:151], v0
	ds_read_b128 v[152:155], v0 offset:1024
	ds_read_b128 v[156:159], v0 offset:2048
	ds_read_b128 v[160:163], v0 offset:3072
	v_lshl_add_u64 v[2:3], v[204:205], 0, s[30:31]
	s_add_i32 m0, s43, 0xc000
	ds_read_b128 v[164:167], v235
	ds_read_b128 v[168:171], v235 offset:1024
	ds_read_b128 v[172:175], v235 offset:2048
	ds_read_b128 v[176:179], v235 offset:3072
	ds_read_b128 v[180:183], v235 offset:4096
	ds_read_b128 v[184:187], v235 offset:5120
	ds_read_b128 v[236:239], v235 offset:6144
	ds_read_b128 v[240:243], v235 offset:7168
	global_load_lds_dwordx4 v[2:3], off
	v_lshl_add_u64 v[2:3], v[206:207], 0, s[30:31]
	s_add_i32 m0, s43, 0xe000
	s_nop 0
	global_load_lds_dwordx4 v[2:3], off
	s_waitcnt vmcnt(8)
	s_waitcnt lgkmcnt(0)
	s_setprio 1
	s_barrier
	v_mfma_f32_16x16x32_bf16 v[116:119], v[132:135], v[164:167], v[116:119]
	v_mfma_f32_16x16x32_bf16 v[116:119], v[136:139], v[168:171], v[116:119]
	v_mfma_f32_16x16x32_bf16 v[120:123], v[140:143], v[164:167], v[120:123]
	v_mfma_f32_16x16x32_bf16 v[120:123], v[144:147], v[168:171], v[120:123]
	v_mfma_f32_16x16x32_bf16 v[104:107], v[140:143], v[172:175], v[104:107]
	v_mfma_f32_16x16x32_bf16 v[104:107], v[144:147], v[176:179], v[104:107]
	v_mfma_f32_16x16x32_bf16 v[100:103], v[132:135], v[172:175], v[100:103]
	v_mfma_f32_16x16x32_bf16 v[100:103], v[136:139], v[176:179], v[100:103]
	v_mfma_f32_16x16x32_bf16 v[76:79], v[132:135], v[180:183], v[76:79]
	v_mfma_f32_16x16x32_bf16 v[76:79], v[136:139], v[184:187], v[76:79]
	v_mfma_f32_16x16x32_bf16 v[80:83], v[140:143], v[180:183], v[80:83]
	v_mfma_f32_16x16x32_bf16 v[80:83], v[144:147], v[184:187], v[80:83]
	v_mfma_f32_16x16x32_bf16 v[48:51], v[140:143], v[236:239], v[48:51]
	v_mfma_f32_16x16x32_bf16 v[48:51], v[144:147], v[240:243], v[48:51]
	v_mfma_f32_16x16x32_bf16 v[44:47], v[132:135], v[236:239], v[44:47]
	v_mfma_f32_16x16x32_bf16 v[44:47], v[136:139], v[240:243], v[44:47]
	v_mfma_f32_16x16x32_bf16 v[124:127], v[148:151], v[164:167], v[124:127]
	v_mfma_f32_16x16x32_bf16 v[124:127], v[152:155], v[168:171], v[124:127]
	v_mfma_f32_16x16x32_bf16 v[128:131], v[156:159], v[164:167], v[128:131]
	v_mfma_f32_16x16x32_bf16 v[128:131], v[160:163], v[168:171], v[128:131]
	v_mfma_f32_16x16x32_bf16 v[112:115], v[156:159], v[172:175], v[112:115]
	v_mfma_f32_16x16x32_bf16 v[112:115], v[160:163], v[176:179], v[112:115]
	v_mfma_f32_16x16x32_bf16 v[108:111], v[148:151], v[172:175], v[108:111]
	v_mfma_f32_16x16x32_bf16 v[108:111], v[152:155], v[176:179], v[108:111]
	v_mfma_f32_16x16x32_bf16 v[92:95], v[148:151], v[180:183], v[92:95]
	v_mfma_f32_16x16x32_bf16 v[92:95], v[152:155], v[184:187], v[92:95]
	v_mfma_f32_16x16x32_bf16 v[96:99], v[156:159], v[180:183], v[96:99]
	v_mfma_f32_16x16x32_bf16 v[96:99], v[160:163], v[184:187], v[96:99]
	v_mfma_f32_16x16x32_bf16 v[72:75], v[156:159], v[236:239], v[72:75]
	v_mfma_f32_16x16x32_bf16 v[72:75], v[160:163], v[240:243], v[72:75]
	s_setprio 2
	s_barrier
	v_mfma_f32_16x16x32_bf16 v[68:71], v[148:151], v[236:239], v[68:71]
	v_mfma_f32_16x16x32_bf16 v[68:71], v[152:155], v[240:243], v[68:71]
	s_setprio 0
	s_add_i32 s65, s65, s41
	v_lshl_add_u64 v[208:209], s[62:63], 0, v[192:193]
	s_mov_b32 m0, s65
	ds_read_b128 v[164:167], v235 offset:16384
	ds_read_b128 v[168:171], v235 offset:17408
	ds_read_b128 v[172:175], v235 offset:18432
	ds_read_b128 v[176:179], v235 offset:19456
	ds_read_b128 v[180:183], v235 offset:20480
	ds_read_b128 v[184:187], v235 offset:21504
	ds_read_b128 v[236:239], v235 offset:22528
	ds_read_b128 v[240:243], v235 offset:23552
	global_load_lds_dwordx4 v[208:209], off
	s_add_i32 m0, s65, 0x2000
	v_lshl_add_u64 v[244:245], s[62:63], 0, v[196:197]
	s_add_u32 s62, s62, s16
	s_addc_u32 s63, s63, 0
	s_add_i32 s64, s64, s41
	global_load_lds_dwordx4 v[244:245], off
	v_lshl_add_u64 v[246:247], s[62:63], 0, v[192:193]
	s_mov_b32 m0, s64
	v_lshl_add_u64 v[248:249], s[62:63], 0, v[196:197]
	global_load_lds_dwordx4 v[246:247], off
	s_add_i32 m0, s64, 0x2000
	v_lshl_add_u64 v[250:251], s[34:35], 0, v[190:191]
	global_load_lds_dwordx4 v[248:249], off
	s_mov_b32 m0, s43
	v_lshl_add_u64 v[212:213], s[34:35], 0, v[194:195]
	global_load_lds_dwordx4 v[250:251], off
	s_mov_b32 m0, s44
	s_nop 0
	global_load_lds_dwordx4 v[212:213], off
	s_waitcnt vmcnt(8)
	s_waitcnt lgkmcnt(0)
	s_setprio 1
	s_barrier
; #define PG8_STAGE(bufoff, gbase, voff) do { _Pragma("unroll") for (int _i = 0; _i < 2; ++_i) \
;         __builtin_amdgcn_global_load_lds((const unsigned*)((const char*)(gbase) + (voff)[_i]), (PG8_LAS unsigned*)(lds + (bufoff) + ldsw + _i * 8192), 16, 0, 0); } while (0)
; #define PG8_LDA(dst, b, h) do { _Pragma("unroll") for (int m = 0; m < 4; ++m) _Pragma("unroll") for (int k = 0; k < 2; ++k) dst[m][k] = *(const PG8_LAS bf16x8*)(lds + PG8_SA(b, h) + aoff + m * 2048 + k * 1024); } while (0)
; #define PG8_LDB(dst, b, h) do { _Pragma("unroll") for (int n = 0; n < 2; ++n) _Pragma("unroll") for (int k = 0; k < 2; ++k) dst[n][k] = *(const PG8_LAS bf16x8*)(lds + PG8_SB(b, h) + boff + n * 2048 + k * 1024); } while (0)
; #define PG8_MMA(ai, bj, At, Bt) do { __builtin_amdgcn_s_setprio(1); _Pragma("unroll") for (int m = 0; m < 4; ++m) _Pragma("unroll") for (int n = 0; n < 2; ++n) _Pragma("unroll") for (int k = 0; k < 2; ++k) \
;         acc[ai][bj][m][n] = __builtin_amdgcn_mfma_f32_16x16x32_bf16(Bt[n][k], At[m][k], acc[ai][bj][m][n], 0, 0, 0); __builtin_amdgcn_s_setprio(0); } while (0)
; #define PG8_WAIT_V(n) asm volatile("s_waitcnt vmcnt(" #n ")" ::: "memory")
; #define PG8_WAIT_L(n) asm volatile("s_waitcnt lgkmcnt(" #n ")" ::: "memory")
; #define PG8_BAR __builtin_amdgcn_s_barrier()
; #define PG8_SCHED __builtin_amdgcn_sched_barrier(0)
; template <class Epi, class Sched, bool ALIGN_EPI = false, bool SP2 = false>
; __device__ __forceinline__ void gemm_phase(PG8_LAS unsigned char* lds, const Gemm g, const Sched& S, const Epi& E) {
;     ...
;             PG8_WAIT_V(8); PG8_WAIT_L(0); PG8_BAR; PG8_MMA(1, 0, At, B0); PG8_MMA(1, 1, At, B1); PG8_BAR; PG8_SCHED;
;             PG8_LDB(B0, 1, 0); PG8_LDB(B1, 1, 1); PG8_SCHED; PG8_LDA(At, 1, 0); PG8_STAGE(PG8_SA(0, 1), a2 + hstep, voffA);
;             PG8_WAIT_V(8); PG8_WAIT_L(0); PG8_BAR; PG8_MMA(0, 0, At, B0); PG8_MMA(0, 1, At, B1); PG8_BAR; PG8_SCHED;
	v_mfma_f32_16x16x32_bf16 v[60:63], v[132:135], v[164:167], v[60:63]
	v_mfma_f32_16x16x32_bf16 v[60:63], v[136:139], v[168:171], v[60:63]
	v_mfma_f32_16x16x32_bf16 v[64:67], v[140:143], v[164:167], v[64:67]
	v_mfma_f32_16x16x32_bf16 v[64:67], v[144:147], v[168:171], v[64:67]
	v_mfma_f32_16x16x32_bf16 v[40:43], v[140:143], v[172:175], v[40:43]
	v_mfma_f32_16x16x32_bf16 v[40:43], v[144:147], v[176:179], v[40:43]
	v_mfma_f32_16x16x32_bf16 v[36:39], v[132:135], v[172:175], v[36:39]
	v_mfma_f32_16x16x32_bf16 v[36:39], v[136:139], v[176:179], v[36:39]
	v_mfma_f32_16x16x32_bf16 v[20:23], v[132:135], v[180:183], v[20:23]
	v_mfma_f32_16x16x32_bf16 v[20:23], v[136:139], v[184:187], v[20:23]
	v_mfma_f32_16x16x32_bf16 v[24:27], v[140:143], v[180:183], v[24:27]
	v_mfma_f32_16x16x32_bf16 v[24:27], v[144:147], v[184:187], v[24:27]
	v_mfma_f32_16x16x32_bf16 v[2:5], v[132:135], v[236:239], v[4:7]
	v_mfma_f32_16x16x32_bf16 v[2:5], v[136:139], v[240:243], v[2:5]
	v_mfma_f32_16x16x32_bf16 v[6:9], v[140:143], v[236:239], v[8:11]
	v_mfma_f32_16x16x32_bf16 v[8:11], v[144:147], v[240:243], v[6:9]
	v_mfma_f32_16x16x32_bf16 v[84:87], v[148:151], v[164:167], v[84:87]
	v_mfma_f32_16x16x32_bf16 v[84:87], v[152:155], v[168:171], v[84:87]
	v_mfma_f32_16x16x32_bf16 v[88:91], v[156:159], v[164:167], v[88:91]
	v_mfma_f32_16x16x32_bf16 v[88:91], v[160:163], v[168:171], v[88:91]
	v_mfma_f32_16x16x32_bf16 v[56:59], v[156:159], v[172:175], v[56:59]
	v_mfma_f32_16x16x32_bf16 v[56:59], v[160:163], v[176:179], v[56:59]
	v_mfma_f32_16x16x32_bf16 v[52:55], v[148:151], v[172:175], v[52:55]
	v_mfma_f32_16x16x32_bf16 v[52:55], v[152:155], v[176:179], v[52:55]
	v_mfma_f32_16x16x32_bf16 v[28:31], v[148:151], v[180:183], v[28:31]
	v_mfma_f32_16x16x32_bf16 v[28:31], v[152:155], v[184:187], v[28:31]
	v_mfma_f32_16x16x32_bf16 v[32:35], v[156:159], v[180:183], v[32:35]
	v_mfma_f32_16x16x32_bf16 v[32:35], v[160:163], v[184:187], v[32:35]
	v_mfma_f32_16x16x32_bf16 v[16:19], v[156:159], v[236:239], v[16:19]
	v_mfma_f32_16x16x32_bf16 v[16:19], v[160:163], v[240:243], v[16:19]
	s_setprio 2
	s_barrier
	v_mfma_f32_16x16x32_bf16 v[12:15], v[148:151], v[236:239], v[12:15]
	v_mfma_f32_16x16x32_bf16 v[12:15], v[152:155], v[240:243], v[12:15]
	s_setprio 0
	s_add_i32 s62, 0, 0x18000
	v_add_u32_e32 v0, s62, v188
	s_add_i32 s63, 0, 0x1c000
	ds_read_b128 v[132:135], v0
	ds_read_b128 v[136:139], v0 offset:1024
	ds_read_b128 v[140:143], v0 offset:2048
	ds_read_b128 v[144:147], v0 offset:3072
	v_add_u32_e32 v0, s63, v188
	ds_read_b128 v[148:151], v0
	ds_read_b128 v[152:155], v0 offset:1024
	ds_read_b128 v[156:159], v0 offset:2048
	ds_read_b128 v[160:163], v0 offset:3072
	s_add_u32 s34, s34, s16
	s_addc_u32 s35, s35, 0
	s_mov_b32 m0, s45
	v_lshl_add_u64 v[6:7], s[34:35], 0, v[190:191]
	ds_read_b128 v[164:167], v235 offset:32768
	ds_read_b128 v[168:171], v235 offset:33792
	ds_read_b128 v[172:175], v235 offset:34816
	ds_read_b128 v[176:179], v235 offset:35840
	ds_read_b128 v[180:183], v235 offset:36864
	ds_read_b128 v[184:187], v235 offset:37888
	ds_read_b128 v[236:239], v235 offset:38912
	ds_read_b128 v[240:243], v235 offset:39936
	global_load_lds_dwordx4 v[6:7], off
	v_lshl_add_u64 v[6:7], s[34:35], 0, v[194:195]
	s_mov_b32 m0, s46
	s_nop 0
	global_load_lds_dwordx4 v[6:7], off
	s_waitcnt vmcnt(8)
	s_waitcnt lgkmcnt(0)
	s_setprio 1
	s_barrier
	v_mfma_f32_16x16x32_bf16 v[116:119], v[132:135], v[164:167], v[116:119]
	v_mfma_f32_16x16x32_bf16 v[116:119], v[136:139], v[168:171], v[116:119]
	v_mfma_f32_16x16x32_bf16 v[120:123], v[140:143], v[164:167], v[120:123]
	v_mfma_f32_16x16x32_bf16 v[120:123], v[144:147], v[168:171], v[120:123]
	v_mfma_f32_16x16x32_bf16 v[104:107], v[140:143], v[172:175], v[104:107]
	v_mfma_f32_16x16x32_bf16 v[104:107], v[144:147], v[176:179], v[104:107]
	v_mfma_f32_16x16x32_bf16 v[100:103], v[132:135], v[172:175], v[100:103]
	v_mfma_f32_16x16x32_bf16 v[100:103], v[136:139], v[176:179], v[100:103]
	v_mfma_f32_16x16x32_bf16 v[76:79], v[132:135], v[180:183], v[76:79]
	v_mfma_f32_16x16x32_bf16 v[76:79], v[136:139], v[184:187], v[76:79]
	v_mfma_f32_16x16x32_bf16 v[80:83], v[140:143], v[180:183], v[80:83]
	v_mfma_f32_16x16x32_bf16 v[80:83], v[144:147], v[184:187], v[80:83]
	v_mfma_f32_16x16x32_bf16 v[48:51], v[140:143], v[236:239], v[48:51]
	v_mfma_f32_16x16x32_bf16 v[48:51], v[144:147], v[240:243], v[48:51]
	v_mfma_f32_16x16x32_bf16 v[44:47], v[132:135], v[236:239], v[44:47]
	v_mfma_f32_16x16x32_bf16 v[44:47], v[136:139], v[240:243], v[44:47]
	v_mfma_f32_16x16x32_bf16 v[124:127], v[148:151], v[164:167], v[124:127]
	v_mfma_f32_16x16x32_bf16 v[124:127], v[152:155], v[168:171], v[124:127]
	v_mfma_f32_16x16x32_bf16 v[128:131], v[156:159], v[164:167], v[128:131]
	v_mfma_f32_16x16x32_bf16 v[128:131], v[160:163], v[168:171], v[128:131]
	v_mfma_f32_16x16x32_bf16 v[112:115], v[156:159], v[172:175], v[112:115]
	v_mfma_f32_16x16x32_bf16 v[112:115], v[160:163], v[176:179], v[112:115]
	v_mfma_f32_16x16x32_bf16 v[108:111], v[148:151], v[172:175], v[108:111]
	v_mfma_f32_16x16x32_bf16 v[108:111], v[152:155], v[176:179], v[108:111]
	v_mfma_f32_16x16x32_bf16 v[92:95], v[148:151], v[180:183], v[92:95]
	v_mfma_f32_16x16x32_bf16 v[92:95], v[152:155], v[184:187], v[92:95]
	v_mfma_f32_16x16x32_bf16 v[96:99], v[156:159], v[180:183], v[96:99]
	v_mfma_f32_16x16x32_bf16 v[96:99], v[160:163], v[184:187], v[96:99]
	v_mfma_f32_16x16x32_bf16 v[72:75], v[156:159], v[236:239], v[72:75]
	v_mfma_f32_16x16x32_bf16 v[72:75], v[160:163], v[240:243], v[72:75]
	s_setprio 2
	s_barrier
; #define PG8_STAGE(bufoff, gbase, voff) do { _Pragma("unroll") for (int _i = 0; _i < 2; ++_i) \
;         __builtin_amdgcn_global_load_lds((const unsigned*)((const char*)(gbase) + (voff)[_i]), (PG8_LAS unsigned*)(lds + (bufoff) + ldsw + _i * 8192), 16, 0, 0); } while (0)
; #define PG8_LDA(dst, b, h) do { _Pragma("unroll") for (int m = 0; m < 4; ++m) _Pragma("unroll") for (int k = 0; k < 2; ++k) dst[m][k] = *(const PG8_LAS bf16x8*)(lds + PG8_SA(b, h) + aoff + m * 2048 + k * 1024); } while (0)
; #define PG8_MMA(ai, bj, At, Bt) do { __builtin_amdgcn_s_setprio(1); _Pragma("unroll") for (int m = 0; m < 4; ++m) _Pragma("unroll") for (int n = 0; n < 2; ++n) _Pragma("unroll") for (int k = 0; k < 2; ++k) \
;         acc[ai][bj][m][n] = __builtin_amdgcn_mfma_f32_16x16x32_bf16(Bt[n][k], At[m][k], acc[ai][bj][m][n], 0, 0, 0); __builtin_amdgcn_s_setprio(0); } while (0)
; #define PG8_WAIT_V(n) asm volatile("s_waitcnt vmcnt(" #n ")" ::: "memory")
; #define PG8_WAIT_L(n) asm volatile("s_waitcnt lgkmcnt(" #n ")" ::: "memory")
; #define PG8_BAR __builtin_amdgcn_s_barrier()
; #define PG8_SCHED __builtin_amdgcn_sched_barrier(0)
; template <class Epi, class Sched, bool ALIGN_EPI = false, bool SP2 = false>
; __device__ __forceinline__ void gemm_phase(PG8_LAS unsigned char* lds, const Gemm g, const Sched& S, const Epi& E) {
;     ...
;             PG8_WAIT_V(8); PG8_WAIT_L(0); PG8_BAR; PG8_MMA(0, 0, At, B0); PG8_MMA(0, 1, At, B1); PG8_BAR; PG8_SCHED;
;             PG8_LDA(At, 1, 1); PG8_STAGE(PG8_SB(1, 0), b3, voffB); PG8_STAGE(PG8_SB(1, 1), b3 + hstep, voffB); PG8_STAGE(PG8_SA(1, 0), a3, voffA);
;             PG8_WAIT_V(8); PG8_WAIT_L(0); PG8_BAR; PG8_MMA(1, 0, At, B0); PG8_MMA(1, 1, At, B1); PG8_BAR; PG8_SCHED;
	v_mfma_f32_16x16x32_bf16 v[68:71], v[148:151], v[236:239], v[68:71]
	v_mfma_f32_16x16x32_bf16 v[68:71], v[152:155], v[240:243], v[68:71]
	s_setprio 0
	s_add_i32 s34, s62, s41
	v_lshl_add_u64 v[6:7], v[208:209], 0, s[92:93]
	s_mov_b32 m0, s34
	ds_read_b128 v[164:167], v235 offset:49152
	ds_read_b128 v[168:171], v235 offset:50176
	ds_read_b128 v[172:175], v235 offset:51200
	ds_read_b128 v[176:179], v235 offset:52224
	ds_read_b128 v[180:183], v235 offset:53248
	ds_read_b128 v[184:187], v235 offset:54272
	ds_read_b128 v[236:239], v235 offset:55296
	ds_read_b128 v[240:243], v235 offset:56320
	global_load_lds_dwordx4 v[6:7], off
	v_lshl_add_u64 v[6:7], v[244:245], 0, s[92:93]
	s_add_i32 m0, s34, 0x2000
	s_add_i32 s34, s63, s41
	global_load_lds_dwordx4 v[6:7], off
	v_lshl_add_u64 v[6:7], v[246:247], 0, s[92:93]
	s_mov_b32 m0, s34
	s_nop 0
	global_load_lds_dwordx4 v[6:7], off
	v_lshl_add_u64 v[6:7], v[248:249], 0, s[92:93]
	s_add_i32 m0, s34, 0x2000
	s_nop 0
	global_load_lds_dwordx4 v[6:7], off
	v_lshl_add_u64 v[6:7], v[250:251], 0, s[92:93]
	s_mov_b32 m0, s51
	s_nop 0
	global_load_lds_dwordx4 v[6:7], off
	v_lshl_add_u64 v[6:7], v[212:213], 0, s[92:93]
	s_mov_b32 m0, s52
	s_nop 0
	global_load_lds_dwordx4 v[6:7], off
	s_waitcnt vmcnt(8)
	s_waitcnt lgkmcnt(0)
	s_setprio 1
	s_barrier
	v_mfma_f32_16x16x32_bf16 v[60:63], v[132:135], v[164:167], v[60:63]
	v_mfma_f32_16x16x32_bf16 v[60:63], v[136:139], v[168:171], v[60:63]
	v_mfma_f32_16x16x32_bf16 v[64:67], v[140:143], v[164:167], v[64:67]
	v_mfma_f32_16x16x32_bf16 v[64:67], v[144:147], v[168:171], v[64:67]
	v_mfma_f32_16x16x32_bf16 v[40:43], v[140:143], v[172:175], v[40:43]
	v_mfma_f32_16x16x32_bf16 v[40:43], v[144:147], v[176:179], v[40:43]
	v_mfma_f32_16x16x32_bf16 v[36:39], v[132:135], v[172:175], v[36:39]
	v_mfma_f32_16x16x32_bf16 v[36:39], v[136:139], v[176:179], v[36:39]
	v_mfma_f32_16x16x32_bf16 v[20:23], v[132:135], v[180:183], v[20:23]
	v_mfma_f32_16x16x32_bf16 v[20:23], v[136:139], v[184:187], v[20:23]
	v_mfma_f32_16x16x32_bf16 v[24:27], v[140:143], v[180:183], v[24:27]
	v_mfma_f32_16x16x32_bf16 v[24:27], v[144:147], v[184:187], v[24:27]
	v_mfma_f32_16x16x32_bf16 v[8:11], v[140:143], v[236:239], v[8:11]
	v_mfma_f32_16x16x32_bf16 v[8:11], v[144:147], v[240:243], v[8:11]
	v_mfma_f32_16x16x32_bf16 v[2:5], v[132:135], v[236:239], v[2:5]
	v_mfma_f32_16x16x32_bf16 v[4:7], v[136:139], v[240:243], v[2:5]
	v_mfma_f32_16x16x32_bf16 v[84:87], v[148:151], v[164:167], v[84:87]
	v_mfma_f32_16x16x32_bf16 v[84:87], v[152:155], v[168:171], v[84:87]
	v_mfma_f32_16x16x32_bf16 v[88:91], v[156:159], v[164:167], v[88:91]
	v_mfma_f32_16x16x32_bf16 v[88:91], v[160:163], v[168:171], v[88:91]
	v_mfma_f32_16x16x32_bf16 v[56:59], v[156:159], v[172:175], v[56:59]
	v_mfma_f32_16x16x32_bf16 v[56:59], v[160:163], v[176:179], v[56:59]
	v_mfma_f32_16x16x32_bf16 v[52:55], v[148:151], v[172:175], v[52:55]
	v_mfma_f32_16x16x32_bf16 v[52:55], v[152:155], v[176:179], v[52:55]
	v_mfma_f32_16x16x32_bf16 v[28:31], v[148:151], v[180:183], v[28:31]
	v_mfma_f32_16x16x32_bf16 v[28:31], v[152:155], v[184:187], v[28:31]
	v_mfma_f32_16x16x32_bf16 v[32:35], v[156:159], v[180:183], v[32:35]
	v_mfma_f32_16x16x32_bf16 v[32:35], v[160:163], v[184:187], v[32:35]
	v_mfma_f32_16x16x32_bf16 v[16:19], v[156:159], v[236:239], v[16:19]
	v_mfma_f32_16x16x32_bf16 v[16:19], v[160:163], v[240:243], v[16:19]
	s_setprio 2
	s_barrier
	v_mfma_f32_16x16x32_bf16 v[12:15], v[148:151], v[236:239], v[12:15]
	v_mfma_f32_16x16x32_bf16 v[12:15], v[152:155], v[240:243], v[12:15]
	s_setprio 0
	s_add_u32 s30, s30, 0x100
	s_addc_u32 s31, s31, 0
	s_cmp_ge_u32 s2, s47
	s_cbranch_scc1 .LBB0_58
	s_mov_b32 s34, s2
	s_branch .LBB0_54
